# attention item loop: windowed-attention items handed out dynamically from a per-layer counter (faster workgroups take more of them); every item still computed once
# baseline (speedup 1.0000x reference)
; DI void phase_attn(const Params& p, int layer, char* lds) {
;     ...
;   for (int g = blockIdx.x; g < N_MLA + N_DIFF + N_SWA; g += gridDim.x) {
;     if (g < N_MLA) { int i = g; attn_item<0>(p, layer, (i & 7) + 8 * (i >> 8), (i >> 3) & 31, lds); }
;     else if (g < N_MLA + N_DIFF) { int i = g - N_MLA; attn_item<1>(p, layer, (i & 7) + 8 * (i >> 8), (i >> 3) & 31, lds); }
;     else { int i = g - N_MLA - N_DIFF; attn_item<2>(p, layer, (i & 7) + 8 * (i >> 8), (i >> 3) & 31, lds); }
;   }
.LBB0_321:
	v_readlane_b32 s4, v254, 62
	s_add_i32 s60, s60, s74
	s_add_i32 s44, s44, s4
	s_cmpk_lt_i32 s60, 0x500
	s_cbranch_scc1 .Ldq_done
	v_readlane_b32 s6, v255, 36
	v_readlane_b32 s7, v255, 37
	v_readlane_b32 s5, v255, 40
	v_mov_b32_e32 v3, 0x23ff0
	v_cmp_eq_u32_e32 vcc, 0, v184
	s_lshl_b32 s5, s5, 2
	s_and_saveexec_b64 s[8:9], vcc
	v_mov_b32_e32 v0, s5
	v_mov_b32_e32 v1, 1
	s_nop 4
	global_atomic_add v2, v0, v1, s[6:7] offset:64 sc0
	s_waitcnt vmcnt(0)
	ds_write_b32 v3, v2
	s_waitcnt lgkmcnt(0)
	s_or_b64 exec, exec, s[8:9]
	s_barrier
	ds_read_b32 v2, v3
	s_waitcnt lgkmcnt(0)
	s_nop 0
	v_readfirstlane_b32 s4, v2
	s_nop 3
	s_add_i32 s60, s4, 0x500
	s_lshl_b32 s44, s60, 5
.Ldq_done:
	s_cmpk_lt_i32 s60, 0x800
	s_cbranch_scc0 .LBB0_506
